# speedup vs baseline: 1.0065x; 1.0065x over previous
; #define WAIT_V(n) asm volatile("s_waitcnt vmcnt(" #n ")" ::: "memory")
; #define BAR __builtin_amdgcn_s_barrier()
; template <int MODE>
; __device__ __forceinline__ void gemm_tile(const int ph, const int which, const int pm, const int pn) {
;     ...
;   __amdgpu_buffer_rsrc_t RA = __builtin_amdgcn_make_buffer_rsrc((void*)A, 0, 0x7ffffff0, 0x00020000);
;   __amdgpu_buffer_rsrc_t RB = __builtin_amdgcn_make_buffer_rsrc((void*)Bt, 0, 0x7ffffff0, 0x00020000);
;   int voff;
;   {
;     int _r, _c;
;     stage_rc(gtid * 16, _r, _c);
;     voff = (_r * K + _c) * 2;
;   }
;   f32x4 acc[2][2][4][2] = {};
;   bf16x8 At[4][2], B0[2][2], B1[2][2];
;   const int nt = K / BK;
;   const int brow = browA;
;   STAGE(SB(0, 0), RB, bcol, 0);
;   STAGE(SA(0, 0), RA, brow, 0);
;   STAGE(SB(0, 1), RB, bcolB, 0);
;   STAGE(SA(0, 1), RA, brow + HALF, 0);
;   if (wr == 1) BAR;
;   WAIT_V(4);
;   BAR;
;   STAGE(SB(1, 0), RB, bcol, 1);
;   STAGE(SA(1, 0), RA, brow, 1);
;   STAGE(SB(1, 1), RB, bcolB, 1);
;   WAIT_V(6);
;     ...
;         const int lr = ai * HALF + wr * 64 + m * 16 + fr;
;         const int gr = browC + lr;
;         const float s = scale[gr];
.LBB0_367:
	v_bfe_i32 v2, v164, 27, 1
	v_lshlrev_b32_e32 v131, 4, v164
	v_lshrrev_b32_e32 v2, 22, v2
	v_add_u32_e32 v2, v131, v2
	v_and_b32_e32 v2, 0xfffffc00, v2
	v_ashrrev_i32_e32 v0, 31, v164
	v_sub_u32_e32 v2, v131, v2
	v_lshrrev_b32_e32 v0, 26, v0
	v_lshrrev_b32_e32 v3, 4, v2
	v_add_u32_e32 v0, v164, v0
	v_bitop3_b32 v3, v3, v2, 32 bitop3:0x6c
	v_ashrrev_i32_e32 v2, 31, v2
	v_ashrrev_i32_e32 v0, 6, v0
	v_lshrrev_b32_e32 v2, 26, v2
	v_lshlrev_b32_e32 v4, 3, v0
	v_add_u32_e32 v2, v3, v2
	v_and_b32_e32 v4, 0x7ffffff0, v4
	v_ashrrev_i32_e32 v2, 6, v2
	v_add_u32_e32 v4, v2, v4
	v_mul_i32_i24_e32 v2, 64, v2
	s_add_i32 s20, s6, s3
	v_lshlrev_b32_e32 v0, 5, v0
	v_sub_u32_e32 v2, v3, v2
	s_add_i32 s16, s2, s3
	v_and_b32_e32 v0, 32, v0
	v_ashrrev_i16_sdwa v2, v223, sext(v2) dst_sel:DWORD dst_unused:UNUSED_PAD src0_sel:DWORD src1_sel:BYTE_0
	s_mul_i32 s2, s20, s26
	v_add_u32_e32 v132, 0x10000, v131
	v_add_u32_sdwa v0, v0, sext(v2) dst_sel:DWORD dst_unused:UNUSED_PAD src0_sel:DWORD src1_sel:WORD_0
	v_mul_lo_u32 v2, s26, v4
	s_lshl_b32 s17, s2, 1
	v_readfirstlane_b32 s2, v132
	v_add_u32_e32 v133, 0x12000, v131
	s_and_b32 s69, s69, 0xffff
	v_add_lshl_u32 v130, v0, v2, 1
	s_mov_b32 m0, s2
	s_lshl_b32 s8, s26, 7
	v_readfirstlane_b32 s3, v133
	buffer_load_dwordx4 v130, s[68:71], s17 offen lds
	s_add_i32 s2, s17, s8
	s_mov_b32 m0, s3
	s_mul_i32 s9, s18, s26
	buffer_load_dwordx4 v130, s[68:71], s2 offen lds
	v_readfirstlane_b32 s2, v131
	v_add_u32_e32 v134, 0x2000, v131
	s_and_b32 s5, s5, 0xffff
	s_mov_b32 s6, s70
	s_mov_b32 s7, s71
	s_lshl_b32 s11, s9, 1
	s_mov_b32 m0, s2
	v_readfirstlane_b32 s3, v134
	buffer_load_dwordx4 v130, s[4:7], s11 offen lds
	s_add_i32 s2, s11, s8
	s_mov_b32 m0, s3
	v_add_u32_e32 v135, 0x14000, v131
	buffer_load_dwordx4 v130, s[4:7], s2 offen lds
	s_mul_i32 s2, s16, s26
	s_lshl_b32 s10, s2, 1
	v_readfirstlane_b32 s2, v135
	v_add_u32_e32 v136, 0x16000, v131
	s_mov_b32 m0, s2
	v_readfirstlane_b32 s3, v136
	v_add_u32_e32 v143, 0x4000, v131
	buffer_load_dwordx4 v130, s[68:71], s10 offen lds
	s_add_i32 s2, s10, s8
	s_mov_b32 m0, s3
	s_add_i32 s9, s9, s8
	v_readfirstlane_b32 s3, v143
	v_add_u32_e32 v144, 0x6000, v131
	buffer_load_dwordx4 v130, s[68:71], s2 offen lds
	s_lshl_b32 s2, s9, 1
	s_mov_b32 m0, s3
	v_readfirstlane_b32 s3, v144
	buffer_load_dwordx4 v130, s[4:7], s2 offen lds
	s_add_i32 s2, s2, s8
	s_mov_b32 m0, s3
	v_ashrrev_i32_e32 v167, 8, v164
	buffer_load_dwordx4 v130, s[4:7], s2 offen lds
	s_load_dwordx2 s[98:99], s[0:1], 0xf8
	v_and_b32_e32 v162, 15, v164
	v_lshl_or_b32 v162, v167, 6, v162
	v_add_u32_e32 v162, s18, v162
	v_mov_b32_e32 v163, 0
	s_waitcnt lgkmcnt(0)
	s_add_u32 s98, s98, 0x3be6000
	s_addc_u32 s99, s99, 0
	v_lshl_add_u64 v[162:163], v[162:163], 2, s[98:99]
	global_load_dword v214, v[162:163], off
	global_load_dword v215, v[162:163], off offset:64
	global_load_dword v217, v[162:163], off offset:128
	global_load_dword v222, v[162:163], off offset:192
	global_load_dword v226, v[162:163], off offset:512
	global_load_dword v227, v[162:163], off offset:576
	global_load_dword v234, v[162:163], off offset:640
	global_load_dword v235, v[162:163], off offset:704
	v_cmp_eq_u32_e32 vcc, 1, v167
	s_and_saveexec_b64 s[2:3], vcc
	s_cbranch_execz .LBB0_369
	s_barrier
; #define WAIT_V(n) asm volatile("s_waitcnt vmcnt(" #n ")" ::: "memory")
; #define BAR __builtin_amdgcn_s_barrier()
; template <int MODE>
; __device__ __forceinline__ void gemm_tile(const int ph, const int which, const int pm, const int pn) {
;     ...
;   const int wid = gtid >> 6, lane = gtid & 63, wr = wid >> 2, wc = wid & 3, fr = lane & 15,
;             fq = lane >> 4;
;   __amdgpu_buffer_rsrc_t RA = __builtin_amdgcn_make_buffer_rsrc((void*)A, 0, 0x7ffffff0, 0x00020000);
;   __amdgpu_buffer_rsrc_t RB = __builtin_amdgcn_make_buffer_rsrc((void*)Bt, 0, 0x7ffffff0, 0x00020000);
;   int voff;
;   {
;     int _r, _c;
;     stage_rc(gtid * 16, _r, _c);
;     voff = (_r * K + _c) * 2;
;   }
;   f32x4 acc[2][2][4][2] = {};
;   bf16x8 At[4][2], B0[2][2], B1[2][2];
;   const int nt = K / BK;
;   const int brow = browA;
;   STAGE(SB(0, 0), RB, bcol, 0);
;   STAGE(SA(0, 0), RA, brow, 0);
;   STAGE(SB(0, 1), RB, bcolB, 0);
;   STAGE(SA(0, 1), RA, brow + HALF, 0);
;   if (wr == 1) BAR;
;   WAIT_V(4);
;   BAR;
;   STAGE(SB(1, 0), RB, bcol, 1);
;   STAGE(SA(1, 0), RA, brow, 1);
;   STAGE(SB(1, 1), RB, bcolB, 1);
;   WAIT_V(6);
;   BAR;
.LBB0_369:
	s_or_b64 exec, exec, s[2:3]
	v_add_u32_e32 v145, 0x18000, v131
	v_add_u32_e32 v146, 0x1a000, v131
	v_readfirstlane_b32 s6, v145
	s_or_b32 s3, s17, 0x80
	s_mov_b32 m0, s6
	v_readfirstlane_b32 s6, v146
	s_waitcnt vmcnt(12)
	s_barrier
	buffer_load_dwordx4 v130, s[68:71], s3 offen lds
	s_add_i32 s3, s3, s8
	s_mov_b32 m0, s6
	v_add_u32_e32 v147, 0x8000, v131
	buffer_load_dwordx4 v130, s[68:71], s3 offen lds
	s_or_b32 s3, s11, 0x80
	v_readfirstlane_b32 s11, v147
	v_add_u32_e32 v148, 0xa000, v131
	s_mov_b32 s6, s70
	s_mov_b32 s7, s71
	s_mov_b32 m0, s11
	v_readfirstlane_b32 s11, v148
	buffer_load_dwordx4 v130, s[4:7], s3 offen lds
	s_add_i32 s3, s3, s8
	s_mov_b32 m0, s11
	v_add_u32_e32 v150, 0x1c000, v131
	buffer_load_dwordx4 v130, s[4:7], s3 offen lds
	s_or_b32 s3, s10, 0x80
	v_readfirstlane_b32 s10, v150
	v_add_u32_e32 v152, 0x1e000, v131
	s_mov_b32 m0, s10
	v_readfirstlane_b32 s10, v152
	buffer_load_dwordx4 v130, s[68:71], s3 offen lds
	s_add_i32 s3, s3, s8
	s_mov_b32 m0, s10
	v_and_b32_e32 v2, 15, v164
	buffer_load_dwordx4 v130, s[68:71], s3 offen lds
	v_bfe_u32 v162, v164, 4, 2
	v_lshlrev_b32_e32 v4, 4, v162
	v_lshlrev_b32_e32 v5, 6, v2
	v_lshlrev_b32_e32 v7, 2, v164
	v_or_b32_e32 v6, v4, v5
	v_and_b32_e32 v7, 32, v7
	s_mov_b32 s3, 0x10000
	v_bitop3_b32 v8, v6, s3, v7 bitop3:0xde
	s_mov_b32 s3, 0x14000
	v_bitop3_b32 v9, v6, s3, v7 bitop3:0xde
	s_mov_b32 s3, 0x18000
	v_bitop3_b32 v10, v6, s3, v7 bitop3:0xde
	s_mov_b32 s3, 0x1c000
	s_lshl_b32 s12, s18, 1
	v_bitop3_b32 v6, v6, s3, v7 bitop3:0xde
	v_lshl_or_b32 v163, v167, 6, v2
	v_lshlrev_b32_e32 v2, 6, v164
	s_add_i32 s3, s12, 0x180
	s_addk_i32 s12, 0x80
	v_bfe_u32 v0, v164, 6, 2
	v_lshlrev_b32_e32 v11, 13, v167
	v_and_b32_e32 v2, 0x3c0, v2
	s_lshl_b32 s11, s16, 1
	s_mul_i32 s17, s26, s12
	s_lshl_b32 s12, s20, 1
	s_lshr_b32 s2, s26, 6
	v_lshlrev_b32_e32 v3, 12, v0
	v_bitop3_b32 v5, v4, v7, v5 bitop3:0x36
	v_bitop3_b32 v4, v2, v7, v4 bitop3:0x36
	v_or_b32_e32 v7, 0x800, v11
	v_or_b32_e32 v12, 0x1000, v11
	v_or_b32_e32 v13, 0x1800, v11
	s_lshl_b32 s13, s26, 1
	s_add_i32 s10, s18, 0x80
	s_addk_i32 s11, 0x80
	s_addk_i32 s12, 0x80
	v_mov_b32_e32 v2, 0
	s_add_i32 s2, s2, -2
	v_add_u32_e32 v151, 0xc000, v131
	v_add_u32_e32 v149, 0xe000, v131
	s_mul_i32 s3, s26, s3
	s_mul_i32 s10, s13, s10
	s_mul_i32 s11, s26, s11
	s_mul_i32 s16, s13, s16
	s_mul_i32 s18, s13, s18
	s_mul_i32 s19, s26, s12
	s_mul_i32 s20, s13, s20
	s_mov_b32 s21, 0
	v_add_u32_e32 v154, v8, v3
	v_add_u32_e32 v141, v5, v11
	v_add_u32_e32 v140, v4, v7
	v_add_u32_e32 v139, v4, v12
	v_add_u32_e32 v138, v4, v13
	v_add_u32_e32 v153, v9, v3
	v_add_u32_e32 v137, v10, v3
	v_add_u32_e32 v142, v6, v3
	s_mov_b32 s22, 0
	v_mov_b32_e32 v3, v2
	v_mov_b32_e32 v4, v2
	v_mov_b32_e32 v5, v2
	v_mov_b32_e32 v6, v2
	v_mov_b32_e32 v7, v2
	v_mov_b32_e32 v8, v2
	v_mov_b32_e32 v9, v2
	v_mov_b32_e32 v18, v2
	v_mov_b32_e32 v19, v2
	v_mov_b32_e32 v20, v2
	v_mov_b32_e32 v21, v2
	v_mov_b32_e32 v30, v2
	v_mov_b32_e32 v31, v2
	v_mov_b32_e32 v32, v2
	v_mov_b32_e32 v33, v2
	v_mov_b32_e32 v42, v2
	v_mov_b32_e32 v43, v2
	v_mov_b32_e32 v44, v2
	v_mov_b32_e32 v45, v2
	v_mov_b32_e32 v54, v2
	v_mov_b32_e32 v55, v2
	v_mov_b32_e32 v56, v2
	v_mov_b32_e32 v57, v2
	v_mov_b32_e32 v66, v2
	v_mov_b32_e32 v67, v2
	v_mov_b32_e32 v68, v2
	v_mov_b32_e32 v69, v2
	v_mov_b32_e32 v78, v2
	v_mov_b32_e32 v79, v2
	v_mov_b32_e32 v80, v2
	v_mov_b32_e32 v81, v2
	v_mov_b32_e32 v10, v2
	v_mov_b32_e32 v11, v2
	v_mov_b32_e32 v12, v2
	v_mov_b32_e32 v13, v2
	v_mov_b32_e32 v22, v2
	v_mov_b32_e32 v23, v2
	v_mov_b32_e32 v24, v2
	v_mov_b32_e32 v25, v2
	v_mov_b32_e32 v34, v2
	v_mov_b32_e32 v35, v2
	v_mov_b32_e32 v36, v2
	v_mov_b32_e32 v37, v2
	v_mov_b32_e32 v46, v2
	v_mov_b32_e32 v47, v2
	v_mov_b32_e32 v48, v2
	v_mov_b32_e32 v49, v2
	v_mov_b32_e32 v58, v2
	v_mov_b32_e32 v59, v2
	v_mov_b32_e32 v60, v2
	v_mov_b32_e32 v61, v2
	v_mov_b32_e32 v70, v2
	v_mov_b32_e32 v71, v2
	v_mov_b32_e32 v72, v2
	v_mov_b32_e32 v73, v2
	v_mov_b32_e32 v82, v2
	v_mov_b32_e32 v83, v2
	v_mov_b32_e32 v84, v2
	v_mov_b32_e32 v85, v2
	v_mov_b32_e32 v94, v2
	v_mov_b32_e32 v95, v2
	v_mov_b32_e32 v96, v2
	v_mov_b32_e32 v97, v2
	v_mov_b32_e32 v14, v2
	v_mov_b32_e32 v15, v2
	v_mov_b32_e32 v16, v2
	v_mov_b32_e32 v17, v2
	v_mov_b32_e32 v26, v2
	v_mov_b32_e32 v27, v2
	v_mov_b32_e32 v28, v2
	v_mov_b32_e32 v29, v2
	v_mov_b32_e32 v38, v2
	v_mov_b32_e32 v39, v2
	v_mov_b32_e32 v40, v2
	v_mov_b32_e32 v41, v2
	v_mov_b32_e32 v50, v2
	v_mov_b32_e32 v51, v2
	v_mov_b32_e32 v52, v2
	v_mov_b32_e32 v53, v2
	v_mov_b32_e32 v62, v2
	v_mov_b32_e32 v63, v2
	v_mov_b32_e32 v64, v2
	v_mov_b32_e32 v65, v2
	v_mov_b32_e32 v74, v2
	v_mov_b32_e32 v75, v2
	v_mov_b32_e32 v76, v2
	v_mov_b32_e32 v77, v2
	v_mov_b32_e32 v86, v2
	v_mov_b32_e32 v87, v2
	v_mov_b32_e32 v88, v2
	v_mov_b32_e32 v89, v2
	v_mov_b32_e32 v98, v2
	v_mov_b32_e32 v99, v2
	v_mov_b32_e32 v100, v2
	v_mov_b32_e32 v101, v2
	v_mov_b32_e32 v90, v2
	v_mov_b32_e32 v91, v2
	v_mov_b32_e32 v92, v2
	v_mov_b32_e32 v93, v2
	v_mov_b32_e32 v102, v2
	v_mov_b32_e32 v103, v2
	v_mov_b32_e32 v104, v2
	v_mov_b32_e32 v105, v2
	v_mov_b32_e32 v106, v2
	v_mov_b32_e32 v107, v2
	v_mov_b32_e32 v108, v2
	v_mov_b32_e32 v109, v2
	v_mov_b32_e32 v110, v2
	v_mov_b32_e32 v111, v2
	v_mov_b32_e32 v112, v2
	v_mov_b32_e32 v113, v2
	v_mov_b32_e32 v114, v2
	v_mov_b32_e32 v115, v2
	v_mov_b32_e32 v116, v2
	v_mov_b32_e32 v117, v2
	v_mov_b32_e32 v118, v2
	v_mov_b32_e32 v119, v2
	v_mov_b32_e32 v120, v2
	v_mov_b32_e32 v121, v2
	v_mov_b32_e32 v122, v2
	v_mov_b32_e32 v123, v2
	v_mov_b32_e32 v124, v2
	v_mov_b32_e32 v125, v2
	v_mov_b32_e32 v126, v2
	v_mov_b32_e32 v127, v2
	v_mov_b32_e32 v128, v2
	v_mov_b32_e32 v129, v2
	s_waitcnt vmcnt(6)

; template <int MODE>
; __device__ __forceinline__ void gemm_tile(const int ph, const int which, const int pm, const int pn) {
;     ...
;     for (int n = 0; n < 2; ++n) {
;       const int j = ecol + wc * 32 + n * 16 + fq * 4;
;       w0[n] = *(const float4*)(cw + j);
;       w1[n] = *(const float4*)(cw + DFF + j);
;       w2[n] = *(const float4*)(cw + 2 * DFF + j);
;       bb[n] = *(const float4*)(cb + j);
;     }
; #pragma unroll
;     for (int ai = 0; ai < 2; ++ai)
; #pragma unroll
;       for (int m = 0; m < 4; ++m) {
;         const int lr = ai * HALF + wr * 64 + m * 16 + fr;
;         const int gr = browC + lr;
;         const float s = scale[gr];
;         rsv[ai][m] = s;
; #pragma unroll
;         for (int n = 0; n < 2; ++n) {
;           const int c = wc * 32 + n * 16 + fq * 4;
;           f32x4 v = acc[ai][0][m][n];
;           uint2 o;
;           o.x = pack2(v[0] * s, v[1] * s);
;           o.y = pack2(v[2] * s, v[3] * s);
;           *(uint2*)(Gs + lr * 264 + c * 2) = o;
;         }
;       }
;     __syncthreads();
.LBB0_403:
	v_mov_b32_e32 v246, 0x3dd2d3e7
	v_mov_b32_e32 v247, 0x3dd2d3e7
	v_mov_b32_e32 v248, v209
	v_mov_b32_e32 v249, v209
	v_mov_b32_e32 v250, 1.0
	v_mov_b32_e32 v251, 1.0
	v_add_u32_e32 v164, s26, v163
	v_ashrrev_i32_e32 v165, 31, v164
	v_lshlrev_b32_e32 v28, 2, v162
	v_lshl_add_u64 v[26:27], v[164:165], 2, s[18:19]
	s_add_u32 s4, s2, 0x2c00
	s_movk_i32 s5, 0x108
	v_lshl_or_b32 v165, v0, 5, v28
	v_mov_b32_e32 v194, v214
	v_mov_b32_e32 v184, v215
	v_mov_b32_e32 v174, v217
	v_mov_b32_e32 v172, v222
	v_mov_b32_e32 v170, v226
	v_lshlrev_b32_e32 v29, 3, v162
	v_mul_lo_u32 v185, v163, s5
	s_addc_u32 s5, s3, 0
	v_or_b32_e32 v28, s6, v165
	v_lshl_or_b32 v0, v0, 6, v29
	v_mov_b32_e32 v168, v227
	v_mov_b32_e32 v166, v234
	v_mov_b32_e32 v162, v235
	v_mov_b32_e32 v214, 0x1000
	v_not_b32_e32 v215, 63
	v_not_b32_e32 v217, 31
	v_mov_b32_e32 v222, 0x3000
	v_mov_b32_e32 v226, 0x20980
	v_mov_b32_e32 v227, 0x10880
	v_mov_b32_e32 v234, 0x800
	v_mov_b32_e32 v235, 0x7fc00000
	s_add_u32 s16, s2, 0x5800
	v_ashrrev_i32_e32 v29, 31, v28
	v_or_b32_e32 v30, 16, v28
	s_addc_u32 s17, s3, 0
	v_lshlrev_b64 v[26:27], 2, v[28:29]
	v_ashrrev_i32_e32 v31, 31, v30
	v_lshl_add_u64 v[28:29], s[2:3], 0, v[26:27]
	v_lshl_add_u64 v[32:33], s[4:5], 0, v[26:27]
	v_lshl_add_u64 v[34:35], s[16:17], 0, v[26:27]
	v_lshl_add_u64 v[36:37], s[8:9], 0, v[26:27]
	v_lshlrev_b64 v[26:27], 2, v[30:31]
	v_lshl_add_u64 v[38:39], s[4:5], 0, v[26:27]
	v_lshl_add_u64 v[176:177], s[16:17], 0, v[26:27]
	global_load_dwordx4 v[42:45], v[32:33], off
	global_load_dwordx4 v[46:49], v[34:35], off
	global_load_dwordx4 v[50:53], v[28:29], off
	s_nop 0
	global_load_dwordx4 v[26:29], v[28:29], off offset:64
	s_nop 0
	global_load_dwordx4 v[54:57], v[36:37], off
	global_load_dwordx4 v[30:33], v[36:37], off offset:64
	s_nop 0
	global_load_dwordx4 v[38:41], v[38:39], off
	s_nop 0
	global_load_dwordx4 v[34:37], v[176:177], off
	v_add_u32_e32 v175, 0x1080, v185
	v_add_u32_e32 v173, 0x2100, v185
	v_add_u32_e32 v195, v0, v185
	v_add_u32_e32 v171, 0x3180, v185
	v_add_u32_e32 v169, 0x8400, v185
	v_add_u32_e32 v210, v0, v175
	v_add_u32_e32 v211, v0, v173
	v_add_u32_e32 v212, v0, v171
	v_add_u32_e32 v213, v0, v169
	v_cmp_gt_i32_e32 vcc, s36, v164
	s_ashr_i32 s7, s6, 31
	s_lshl_b64 s[2:3], s[6:7], 1
	s_add_u32 s2, s10, s2
	s_addc_u32 s3, s11, s3
	s_waitcnt vmcnt(15)
	v_pk_mul_f32 v[206:207], v[106:107], v[194:195] op_sel_hi:[1,0]
	v_pk_mul_f32 v[204:205], v[108:109], v[194:195] op_sel_hi:[1,0]
	v_pk_mul_f32 v[202:203], v[110:111], v[194:195] op_sel_hi:[1,0]
	v_pk_mul_f32 v[200:201], v[112:113], v[194:195] op_sel_hi:[1,0]
	s_waitcnt vmcnt(13)
	v_pk_mul_f32 v[182:183], v[126:127], v[174:175] op_sel_hi:[1,0]
	v_pk_mul_f32 v[180:181], v[128:129], v[174:175] op_sel_hi:[1,0]
	s_waitcnt vmcnt(12)
	v_pk_mul_f32 v[178:179], v[130:131], v[172:173] op_sel_hi:[1,0]
	v_pk_mul_f32 v[176:177], v[132:133], v[172:173] op_sel_hi:[1,0]
	v_pk_mul_f32 v[134:135], v[134:135], v[172:173] op_sel_hi:[1,0]
	v_pk_mul_f32 v[132:133], v[136:137], v[172:173] op_sel_hi:[1,0]
	v_pk_mul_f32 v[198:199], v[114:115], v[184:185] op_sel_hi:[1,0]
	v_pk_mul_f32 v[196:197], v[116:117], v[184:185] op_sel_hi:[1,0]
	v_pk_mul_f32 v[192:193], v[118:119], v[184:185] op_sel_hi:[1,0]
	v_pk_mul_f32 v[190:191], v[120:121], v[184:185] op_sel_hi:[1,0]
	v_pk_mul_f32 v[188:189], v[122:123], v[174:175] op_sel_hi:[1,0]
	v_pk_mul_f32 v[186:187], v[124:125], v[174:175] op_sel_hi:[1,0]
	s_waitcnt vmcnt(11)
	v_pk_mul_f32 v[130:131], v[158:159], v[170:171] op_sel_hi:[1,0]
	v_cvt_pk_bf16_f32 v106, v206, v207
	v_cvt_pk_bf16_f32 v107, v204, v205
	v_cvt_pk_bf16_f32 v108, v202, v203
	v_cvt_pk_bf16_f32 v109, v200, v201
	v_cvt_pk_bf16_f32 v116, v182, v183
	v_cvt_pk_bf16_f32 v117, v180, v181
	v_cvt_pk_bf16_f32 v118, v178, v179
	v_cvt_pk_bf16_f32 v119, v176, v177
	v_cvt_pk_bf16_f32 v120, v134, v135
	v_cvt_pk_bf16_f32 v121, v132, v133
	v_pk_mul_f32 v[128:129], v[160:161], v[170:171] op_sel_hi:[1,0]
	v_pk_mul_f32 v[126:127], v[154:155], v[170:171] op_sel_hi:[1,0]
	v_pk_mul_f32 v[124:125], v[156:157], v[170:171] op_sel_hi:[1,0]
	v_cvt_pk_bf16_f32 v110, v198, v199
	v_cvt_pk_bf16_f32 v111, v196, v197
	v_cvt_pk_bf16_f32 v112, v192, v193
	v_cvt_pk_bf16_f32 v113, v190, v191
	v_cvt_pk_bf16_f32 v114, v188, v189
	v_cvt_pk_bf16_f32 v115, v186, v187
	ds_write2_b64 v195, v[106:107], v[108:109] offset1:4
	ds_write2_b64 v210, v[110:111], v[112:113] offset1:4
	ds_write2_b64 v211, v[114:115], v[116:117] offset1:4
	ds_write2_b64 v212, v[118:119], v[120:121] offset1:4
	v_cvt_pk_bf16_f32 v106, v130, v131
	v_cvt_pk_bf16_f32 v107, v128, v129
	v_cvt_pk_bf16_f32 v108, v126, v127
	v_cvt_pk_bf16_f32 v109, v124, v125
	v_add_u32_e32 v154, 0x9480, v185
	s_waitcnt vmcnt(10)
	v_pk_mul_f32 v[122:123], v[150:151], v[168:169] op_sel_hi:[1,0]
	v_pk_mul_f32 v[120:121], v[152:153], v[168:169] op_sel_hi:[1,0]
	v_pk_mul_f32 v[118:119], v[146:147], v[168:169] op_sel_hi:[1,0]
	v_pk_mul_f32 v[116:117], v[148:149], v[168:169] op_sel_hi:[1,0]
	ds_write2_b64 v213, v[106:107], v[108:109] offset1:4
	v_add_u32_e32 v110, v0, v154
	v_cvt_pk_bf16_f32 v106, v122, v123
	v_cvt_pk_bf16_f32 v107, v120, v121
	v_cvt_pk_bf16_f32 v108, v118, v119
	v_cvt_pk_bf16_f32 v109, v116, v117
	ds_write2_b64 v110, v[106:107], v[108:109] offset1:4
	v_add_u32_e32 v146, 0xa500, v185
	s_waitcnt vmcnt(9)
	v_pk_mul_f32 v[114:115], v[142:143], v[166:167] op_sel_hi:[1,0]
	v_pk_mul_f32 v[112:113], v[144:145], v[166:167] op_sel_hi:[1,0]
	v_pk_mul_f32 v[110:111], v[138:139], v[166:167] op_sel_hi:[1,0]
	v_pk_mul_f32 v[108:109], v[140:141], v[166:167] op_sel_hi:[1,0]
	v_add_u32_e32 v147, v0, v146
	v_cvt_pk_bf16_f32 v106, v114, v115
	v_cvt_pk_bf16_f32 v107, v112, v113
	v_cvt_pk_bf16_f32 v136, v110, v111
	v_cvt_pk_bf16_f32 v137, v108, v109
	ds_write2_b64 v147, v[106:107], v[136:137] offset1:4
	v_add_u32_e32 v138, 0xb580, v185
	s_waitcnt vmcnt(8)
	v_pk_mul_f32 v[106:107], v[102:103], v[162:163] op_sel_hi:[1,0]
	v_pk_mul_f32 v[104:105], v[104:105], v[162:163] op_sel_hi:[1,0]
	v_pk_mul_f32 v[102:103], v[98:99], v[162:163] op_sel_hi:[1,0]
	v_pk_mul_f32 v[98:99], v[100:101], v[162:163] op_sel_hi:[1,0]
	v_add_u32_e32 v0, v0, v138
	v_cvt_pk_bf16_f32 v136, v106, v107
	v_cvt_pk_bf16_f32 v137, v104, v105
	v_cvt_pk_bf16_f32 v140, v102, v103
	v_cvt_pk_bf16_f32 v141, v98, v99
	ds_write2_b64 v0, v[136:137], v[140:141] offset1:4
	v_cndmask_b32_e32 v0, v224, v225, vcc
	v_and_b32_e32 v100, v0, v164
	v_cmp_lt_i32_e32 vcc, 0, v163
	v_cmp_eq_u32_e64 s[6:7], 0, v100
	v_cmp_ne_u32_e64 s[4:5], 0, v100
	s_or_b64 s[6:7], vcc, s[6:7]
	s_waitcnt lgkmcnt(0)
	s_barrier
; __device__ __forceinline__ float lo2f(unsigned u) { return __uint_as_float(u << 16); }
; __device__ __forceinline__ float hi2f(unsigned u) { return __uint_as_float(u & 0xffff0000u); }
; template <int MODE>
; __device__ __forceinline__ void gemm_tile(const int ph, const int which, const int pm, const int pn) {
;     ...
; #pragma unroll
;     for (int ai = 0; ai < 2; ++ai)
; #pragma unroll
;       for (int m = 0; m < 4; ++m) {
;         const int lr = ai * HALF + wr * 64 + m * 16 + fr;
;         const int gr = browC + lr;
;         const int L = gr < 32768 ? 2048 : 4096;
;         const int pos = gr & (L - 1);
;         if ((lr >= 1 || pos == 0) && (lr <= 254 || pos == L - 1)) {
;           const float s = rsv[ai][m];
;           bf16_t* arow = C + (size_t)gr * DFF;
;   #pragma unroll
;         for (int n = 0; n < 2; ++n) {
;             const int c = wc * 32 + n * 16 + fq * 4;
;             uint2 pu = make_uint2(0u, 0u), nu = make_uint2(0u, 0u);
;             if (pos != 0) pu = *(const uint2*)(Gs + (lr - 1) * 264 + c * 2);
;             if (pos != L - 1) nu = *(const uint2*)(Gs + (lr + 1) * 264 + c * 2);
;             f32x4 g = acc[ai][0][m][n], v = acc[ai][1][m][n];
;             float g0 = w0[n].x * lo2f(pu.x) + w1[n].x * (g[0] * s) + w2[n].x * lo2f(nu.x) + bb[n].x;
;             float g1 = w0[n].y * hi2f(pu.x) + w1[n].y * (g[1] * s) + w2[n].y * hi2f(nu.x) + bb[n].y;
;             float g2 = w0[n].z * lo2f(pu.y) + w1[n].z * (g[2] * s) + w2[n].z * lo2f(nu.y) + bb[n].z;
;             float g3 = w0[n].w * hi2f(pu.y) + w1[n].w * (g[3] * s) + w2[n].w * hi2f(nu.y) + bb[n].w;
;             uint2 o;
;             o.x = pack2(gelu_f(g0) * (v[0] * s), gelu_f(g1) * (v[1] * s));
;             o.y = pack2(gelu_f(g2) * (v[2] * s), gelu_f(g3) * (v[3] * s));
;             *(uint2*)(arow + ecol + c) = o;
;           }
	s_and_saveexec_b64 s[10:11], s[6:7]
	s_cbranch_execz .LBB0_414
	s_movk_i32 s6, 0xff
	v_cmp_gt_i32_e64 s[6:7], s6, v163
	v_cmp_eq_u32_e64 s[8:9], v100, v0
	v_cmp_ne_u32_e32 vcc, v100, v0
	s_or_b64 s[6:7], s[6:7], s[8:9]
	s_and_b64 exec, exec, s[6:7]
	s_cbranch_execz .LBB0_414
	v_add_u32_e32 v139, 0xfffffef8, v185
	v_mov_b32_e32 v100, 0
	v_mov_b32_e32 v136, 0
	v_mov_b32_e32 v137, 0
	s_and_saveexec_b64 s[6:7], s[4:5]
	v_lshl_add_u32 v0, v165, 1, v139
	ds_read_b64 v[136:137], v0
	s_or_b64 exec, exec, s[6:7]
	v_mov_b32_e32 v101, 0
	s_and_saveexec_b64 s[6:7], vcc
	v_lshl_add_u32 v0, v165, 1, v185
	ds_read_b64 v[100:101], v0 offset:264
	s_or_b64 exec, exec, s[6:7]
	s_waitcnt lgkmcnt(0)
	v_lshlrev_b32_e32 v142, 16, v136
	v_and_b32_e32 v143, 0xffff0000, v136
	s_waitcnt vmcnt(5)
	v_pk_mul_f32 v[142:143], v[50:51], v[142:143]
	v_lshlrev_b32_e32 v144, 16, v100
	v_pk_fma_f32 v[142:143], v[42:43], v[206:207], v[142:143]
	v_and_b32_e32 v145, 0xffff0000, v100
	v_pk_fma_f32 v[142:143], v[46:47], v[144:145], v[142:143]
	v_mov_b32_e32 v195, v194
	s_waitcnt vmcnt(3)
	v_pk_add_f32 v[142:143], v[54:55], v[142:143]
	v_pk_mul_f32 v[94:95], v[94:95], v[194:195]
	v_pk_mul_f32 v[144:145], v[142:143], v[142:143]
	v_lshlrev_b32_e32 v136, 16, v137
	v_and_b32_e32 v137, 0xffff0000, v137
	v_mov_b64_e32 v[140:141], s[2:3]
	s_movk_i32 s6, 0x1600
	v_pk_mul_f32 v[96:97], v[96:97], v[194:195]
	v_mad_i64_i32 v[140:141], s[6:7], v164, s6, v[140:141]
	v_pk_fma_f32 v[144:145], v[144:145], v[246:247], v[248:249]
	s_nop 0
	v_pk_mul_f32 v[144:145], v[144:145], v[142:143] neg_lo:[0,1] neg_hi:[0,1]
	s_nop 0
	v_exp_f32_e32 v144, v144
	v_exp_f32_e32 v145, v145
	s_nop 0
	v_pk_add_f32 v[144:145], v[144:145], v[250:251]
	s_nop 0
	v_rcp_f32_e32 v144, v144
	v_rcp_f32_e32 v145, v145
	s_nop 0
	s_nop 0
	v_pk_mul_f32 v[142:143], v[142:143], v[144:145]
	s_nop 0
	v_pk_mul_f32 v[94:95], v[94:95], v[142:143]
	s_nop 0
	v_cvt_pk_bf16_f32 v100, v94, v95
	v_pk_mul_f32 v[94:95], v[52:53], v[136:137]
	v_lshlrev_b32_e32 v136, 16, v101
	v_pk_fma_f32 v[94:95], v[44:45], v[204:205], v[94:95]
	v_and_b32_e32 v137, 0xffff0000, v101
	v_pk_fma_f32 v[94:95], v[48:49], v[136:137], v[94:95]
	s_nop 0
	v_pk_add_f32 v[94:95], v[56:57], v[94:95]
	s_nop 0
	v_pk_mul_f32 v[136:137], v[94:95], v[94:95]
	s_nop 0
	s_nop 0
	s_nop 0
	v_pk_fma_f32 v[136:137], v[136:137], v[246:247], v[248:249]
	s_nop 0
	v_pk_mul_f32 v[136:137], v[136:137], v[94:95] neg_lo:[0,1] neg_hi:[0,1]
	s_nop 0
	v_exp_f32_e32 v136, v136
	v_exp_f32_e32 v137, v137
	s_nop 0
	v_pk_add_f32 v[136:137], v[136:137], v[250:251]
	s_nop 0
	v_rcp_f32_e32 v136, v136
	v_rcp_f32_e32 v137, v137
	s_nop 0
	v_lshlrev_b32_e32 v0, 1, v165
	v_pk_mul_f32 v[94:95], v[94:95], v[136:137]
	s_nop 0
	v_pk_mul_f32 v[94:95], v[96:97], v[94:95]
	v_mov_b32_e32 v96, 0
	v_cvt_pk_bf16_f32 v101, v94, v95
	v_lshl_add_u64 v[94:95], v[140:141], 0, v[0:1]
	global_store_dwordx2 v[94:95], v[100:101], off
	v_or_b32_e32 v0, 16, v165
	v_mov_b32_e32 v100, 0
	v_mov_b32_e32 v101, 0
	s_and_saveexec_b64 s[6:7], s[4:5]
	v_lshl_add_u32 v97, v0, 1, v139
	ds_read_b64 v[100:101], v97
	s_or_b64 exec, exec, s[6:7]
	v_mov_b32_e32 v97, 0
	s_and_saveexec_b64 s[4:5], vcc
	v_lshl_add_u32 v0, v0, 1, v185
	ds_read_b64 v[96:97], v0 offset:264
	s_or_b64 exec, exec, s[4:5]
	s_waitcnt lgkmcnt(0)
	v_lshlrev_b32_e32 v136, 16, v100
	v_and_b32_e32 v137, 0xffff0000, v100
	v_pk_mul_f32 v[136:137], v[26:27], v[136:137]
	v_lshlrev_b32_e32 v140, 16, v96
	s_waitcnt vmcnt(2)
	v_pk_fma_f32 v[136:137], v[38:39], v[202:203], v[136:137]
	v_and_b32_e32 v141, 0xffff0000, v96
	s_waitcnt vmcnt(1)
	v_pk_fma_f32 v[136:137], v[34:35], v[140:141], v[136:137]
	v_lshlrev_b32_e32 v100, 16, v101
	v_pk_add_f32 v[136:137], v[30:31], v[136:137]
	v_and_b32_e32 v101, 0xffff0000, v101
	v_pk_mul_f32 v[140:141], v[136:137], v[136:137]
	v_pk_mul_f32 v[100:101], v[28:29], v[100:101]
	v_pk_fma_f32 v[100:101], v[40:41], v[200:201], v[100:101]
	v_lshlrev_b32_e32 v96, 16, v97
	v_and_b32_e32 v97, 0xffff0000, v97
	v_pk_fma_f32 v[96:97], v[36:37], v[96:97], v[100:101]
	v_pk_mul_f32 v[90:91], v[90:91], v[194:195]
	v_pk_add_f32 v[96:97], v[32:33], v[96:97]
	v_pk_mul_f32 v[100:101], v[96:97], v[96:97]
	v_pk_fma_f32 v[140:141], v[140:141], v[246:247], v[248:249]
	s_nop 0
	v_pk_mul_f32 v[140:141], v[140:141], v[136:137] neg_lo:[0,1] neg_hi:[0,1]
	s_nop 0
	v_exp_f32_e32 v140, v140
	v_exp_f32_e32 v141, v141
	s_nop 0
	v_pk_add_f32 v[140:141], v[140:141], v[250:251]
	s_nop 0
	v_rcp_f32_e32 v140, v140
	v_rcp_f32_e32 v141, v141
	s_nop 0
	v_pk_mul_f32 v[136:137], v[136:137], v[140:141]
	v_pk_mul_f32 v[92:93], v[92:93], v[194:195]
	v_pk_mul_f32 v[90:91], v[90:91], v[136:137]
	v_cvt_pk_bf16_f32 v90, v90, v91
	v_pk_fma_f32 v[100:101], v[100:101], v[246:247], v[248:249]
	s_nop 0
	v_pk_mul_f32 v[100:101], v[100:101], v[96:97] neg_lo:[0,1] neg_hi:[0,1]
	s_nop 0
	v_exp_f32_e32 v100, v100
	v_exp_f32_e32 v101, v101
	s_nop 0
	v_pk_add_f32 v[100:101], v[100:101], v[250:251]
	s_nop 0
	v_rcp_f32_e32 v100, v100
	v_rcp_f32_e32 v101, v101
	s_nop 0
	s_nop 0
	v_pk_mul_f32 v[96:97], v[96:97], v[100:101]
	s_nop 0
	v_pk_mul_f32 v[92:93], v[92:93], v[96:97]
	s_nop 0
	v_cvt_pk_bf16_f32 v91, v92, v93
	global_store_dwordx2 v[94:95], v[90:91], off offset:32
